# XCD grid barrier: non-leader workgroups acquire with an L1-only invalidate (the XCD leader already invalidated the L2 before releasing them)
# baseline (speedup 1.0000x reference)
.LBB0_1194:
	s_or_b64 exec, exec, s[4:5]
	s_waitcnt vmcnt(0)
	buffer_inv sc0
	s_waitcnt vmcnt(0)
